# speedup vs baseline: 1.0376x; 1.0058x over previous
; __device__ __forceinline__ int v_st(int k, int c) { const int kk = (k & ~0xC) | ((k & 4) << 1) | ((k & 8) >> 1); return ((kk >> 3) * 2 + (c >> 5)) * 512 + ((kk & 7) * 32 + (c & 31)) * 2; }
; __device__ __forceinline__ int v_rd_base(int lane) { return ((lane & 3) << 3) | (((lane >> 2) & 3) << 6) | (((lane >> 4) & 1) << 5) | (((lane >> 5) & 1) << 8); }
; #define SLOADP(i, Kp, Vp, t) do { const char* kp = (const char*)(Kp) + (long)(t) * (64 * 192); const char* vp = (const char*)(Vp) + (long)(t) * (64 * 128); \
;     sr_[i].k0 = *reinterpret_cast<const bf16x8*>(kp + kc0 * 16); sr_[i].k1 = *reinterpret_cast<const bf16x8*>(kp + kc1 * 16); \
;     sr_[i].v0 = *reinterpret_cast<const bf16x8*>(vp + tid * 16); } while (0)
; __device__ __forceinline__ void attn_phase(const bf16* __restrict__ qbase, const bf16* __restrict__ Kbase, const bf16* __restrict__ Vbase, bf16* __restrict__ mixbase) {
;     ...
;   const int tid = threadIdx.x, wid = tid >> 6, lane = tid & 63, r32 = lane & 31, hi = lane >> 5;
;   char* V_lds = lds + ATT_V0; char* K_lds = lds + ATT_K0;
;   float* wsf = (float*)(lds + ATT_WS) + wid * 64; float* al_l = wsf + 32;
;   const int kc0 = tid, kc1 = 512 + (tid & 255);
;   const int kst0 = (kc0 / 12) * KPITCH + (kc0 % 12) * 16, kst1 = (kc1 / 12) * KPITCH + (kc1 % 12) * 16;
;   const int vst = v_st(tid >> 3, (tid & 7) * 8);
;   const int vb0 = (int)(uintptr_t)V_lds + v_rd_base(lane);
;   const short one_ = (r32 == 0) ? (short)0x3F80 : (short)0; const bf16x8 ones = {one_, one_, one_, one_, one_, one_, one_, one_};
;   struct { bf16x8 k0, k1, v0; } sr_[2];
;   bf16x8 qr[6];
;   constexpr int SE = 0, SO = 1;
;     ...
;   const bf16 *Qw, *Kh, *Vh; bf16* Ob;
;   ITEM_PTRS(it, Qw, Kh, Vh, Ob);
;   #pragma unroll
;   for (int d0 = 0; d0 < 6; ++d0) qr[d0] = *reinterpret_cast<const bf16x8*>(Qw + d0 * 16);
;   SLOADP(SO, Kh, Vh, 0); SLOADP(SE, Kh, Vh, 1);
;   if (wid >= 4) __builtin_amdgcn_s_setprio(1);
.LBB0_505:
	s_or_b64 exec, exec, s[0:1]
	v_readlane_b32 s82, v254, 36
	v_readlane_b32 s84, v254, 39
	s_cmpk_lt_i32 s95, 0xc00
	v_readlane_b32 s83, v254, 37
	v_readlane_b32 s77, v254, 38
	v_readlane_b32 s85, v254, 40
	s_barrier
	s_cbranch_scc0 .LBB0_542
	s_movk_i32 s0, 0x200
	v_or_b32_sdwa v3, v252, s0 dst_sel:DWORD dst_unused:UNUSED_PAD src0_sel:BYTE_0 src1_sel:DWORD
	s_ashr_i32 s6, s95, 3
	s_ashr_i32 s0, s95, 6
	s_lshl_b32 s5, s95, 8
	v_and_b32_e32 v0, 31, v252
	v_lshrrev_b32_e32 v2, 1, v252
	s_and_b32 s4, s6, 7
	s_ashr_i32 s1, s0, 31
	s_mul_i32 s2, s0, 0x810
	s_and_b32 s5, s5, 0x700
	v_add_u32_e32 v4, 16, v0
	v_and_b32_e32 v2, 0x1e0, v2
	v_mov_b32_e32 v165, 0
	s_mul_hi_i32 s3, s0, 0x810
	s_add_u32 s2, s5, s2
	v_add_u32_e32 v162, v4, v2
	v_mov_b32_e32 v163, v165
	s_addc_u32 s3, 0, s3
	v_lshl_add_u64 v[4:5], s[2:3], 0, v[162:163]
	s_movk_i32 s8, 0x600
	v_mov_b64_e32 v[6:7], s[34:35]
	s_mov_b32 s40, 0
	v_mad_u64_u32 v[6:7], s[2:3], v4, s8, v[6:7]
	v_mad_i32_i24 v7, v5, s8, v7
	s_mul_i32 s2, s4, 0xc0
	s_mov_b32 s3, s40
	v_lshrrev_b32_e32 v1, 5, v193
	v_lshl_add_u64 v[168:169], v[6:7], 0, s[2:3]
	s_mul_hi_i32 s2, s6, 0x63000
	s_mul_i32 s3, s6, 0x63000
	s_mul_hi_i32 s9, s6, 0x42000
	s_mul_i32 s10, s6, 0x42000
	v_readlane_b32 s6, v254, 23
	v_lshlrev_b32_e32 v170, 4, v1
	v_mov_b32_e32 v171, v165
	v_readlane_b32 s7, v254, 24
	s_add_u32 s6, s6, s3
	v_lshl_add_u64 v[4:5], v[168:169], 0, v[170:171]
	s_addc_u32 s7, s7, s2
	global_load_dwordx4 v[80:83], v[4:5], off
	global_load_dwordx4 v[84:87], v[4:5], off offset:32
	global_load_dwordx4 v[88:91], v[4:5], off offset:64
	global_load_dwordx4 v[92:95], v[4:5], off offset:96
	global_load_dwordx4 v[96:99], v[4:5], off offset:128
	global_load_dwordx4 v[100:103], v[4:5], off offset:160
	s_add_u32 s60, s64, s10
	v_lshlrev_b32_e32 v160, 4, v252
	v_mov_b32_e32 v161, v165
	s_addc_u32 s61, s65, s9
	v_lshl_add_u64 v[4:5], s[60:61], 0, v[160:161]
	s_add_u32 s2, s6, 0x3000
	v_lshlrev_b32_e32 v166, 4, v3
	s_addc_u32 s3, s7, 0
	v_add_co_u32_e32 v4, vcc, 0x2000, v4
	global_load_dwordx4 v[132:135], v160, s[6:7]
	global_load_dwordx4 v[136:139], v160, s[60:61]
	global_load_dwordx4 v[140:143], v166, s[6:7]
	global_load_dwordx4 v[104:107], v160, s[2:3]
	v_addc_co_u32_e32 v5, vcc, 0, v5, vcc
	global_load_dwordx4 v[108:111], v166, s[2:3]
	global_load_dwordx4 v[112:115], v[4:5], off
	s_movk_i32 s2, 0xff
	v_lshlrev_b32_e32 v4, 3, v1
	v_cmp_lt_u32_e32 vcc, s2, v252
	s_and_saveexec_b64 s[2:3], vcc
	s_setprio 1
	s_or_b64 exec, exec, s[2:3]
	s_lshl_b64 s[0:1], s[0:1], 22
	s_add_u32 s0, s58, s0
	s_addc_u32 s1, s59, s1
	s_lshl_b32 s2, s5, 11
	s_add_u32 s0, s0, s2
	v_lshrrev_b32_e32 v7, 3, v252
	v_lshrrev_b32_e32 v8, 2, v252
	s_addc_u32 s1, s1, 0
	s_lshl_b32 s2, s4, 7
	v_and_b32_e32 v7, 0x70, v7
	v_and_b32_e32 v8, 8, v8
	v_and_b32_e32 v10, 4, v252
	s_add_u32 s0, s0, s2
	v_lshrrev_b32_e32 v9, 4, v252
	v_or3_b32 v7, v7, v8, v10
	v_bfe_u32 v8, v252, 3, 2
	s_addc_u32 s1, s1, 0
	v_and_or_b32 v8, v9, 4, v8
	v_and_b32_e32 v9, 48, v160
	s_add_u32 s72, s0, 0x400
	v_lshl_or_b32 v8, v8, 6, v9
	v_lshlrev_b32_e32 v9, 3, v252
	v_lshlrev_b32_e32 v11, 1, v252
	s_addc_u32 s73, s1, 0
	v_and_b32_e32 v5, 0x3c0, v252
	v_mul_u32_u24_e32 v6, 0x1556, v3
	v_and_b32_e32 v10, 0xc0, v160
	v_and_b32_e32 v11, 32, v11
	v_and_b32_e32 v9, 0x118, v9
	v_lshl_add_u32 v171, v5, 2, 0
	v_mul_u32_u24_e32 v5, 0x1556, v252
	v_lshrrev_b32_e32 v6, 16, v6
	v_or3_b32 v9, v11, v10, v9
	v_mov_b32_e32 v10, 0x3f80
	v_and_b32_e32 v116, 15, v252
	v_bfe_u32 v117, v252, 4, 1
	v_cmp_eq_u32_e32 vcc, v116, v117
	s_cmp_lg_u32 0, -1
	s_movk_i32 s1, 0xd0
	v_lshlrev_b32_e32 v174, 13, v1
	v_mov_b32_e32 v1, 4
	v_lshrrev_b32_e32 v5, 16, v5
	v_cndmask_b32_e32 v10, 0, v10, vcc
	v_add_lshl_u32 v3, v3, v6, 4
	v_lshl_or_b32 v6, v7, 7, v8
	s_cselect_b32 s0, 0, 0
	v_mad_u32_u24 v7, v0, s1, 0
	s_mov_b32 s1, 0x5040100
	v_and_b32_e32 v8, 32, v252
	v_lshlrev_b32_sdwa v178, v1, v252 dst_sel:DWORD dst_unused:UNUSED_PAD src0_sel:DWORD src1_sel:BYTE_0
	v_mbcnt_hi_u32_b32 v1, -1, v210
	v_add_lshl_u32 v5, v252, v5, 4
	v_add_u32_e32 v212, s0, v9
	v_perm_b32 v116, v10, v10, s1
	s_addk_i32 s0, 0x2000
	v_and_or_b32 v1, v1, 64, v8
	v_mov_b32_e32 v167, v165
	v_mov_b32_e32 v117, v116
	v_mov_b32_e32 v118, v116
	v_mov_b32_e32 v119, v116
	v_cmp_gt_u32_e64 s[4:5], 32, v193
	v_lshl_add_u32 v213, v0, 2, v171
	v_add_u32_e32 v214, s0, v9
	v_lshlrev_b32_e32 v172, 11, v2
	v_mov_b32_e32 v173, v165
	v_mov_b32_e32 v175, v165
	s_mov_b32 s3, 0x8000
	v_or_b32_e32 v176, 0x8000, v160
	v_mov_b32_e32 v177, v161
	v_mov_b32_e32 v179, v165
	s_mov_b32 s9, 0x429cc470
	s_mov_b32 s2, 0x3e16c740
	s_movk_i32 s12, 0x4000
	s_mov_b64 s[10:11], 0x2000
	s_mov_b32 s13, 0x9000
	s_mov_b32 s16, 0xc000
	s_mov_b64 s[14:15], 0x4000
	v_lshlrev_b32_e32 v215, 2, v1
	v_lshlrev_b32_e32 v180, 1, v0
	s_movk_i32 s17, 0x1000
	s_movk_i32 s33, 0x5000
	s_mov_b32 s62, 0xd000
	v_add_u32_e32 v216, 0, v6
	v_add_u32_e32 v217, 0, v5
	v_add_u32_e32 v218, 0, v3
	v_add_u32_e32 v219, v7, v170
	v_mov_b32_e32 v220, 0xf149f2ca
	v_lshlrev_b32_e32 v164, 1, v4
	s_mov_b32 s63, 0
	s_mov_b64 s[68:69], s[72:73]
	s_mov_b64 s[30:31], s[60:61]
	s_mov_b64 s[28:29], s[6:7]
	v_bfe_u32 v251, v252, 4, 2
	v_lshlrev_b32_e32 v251, 4, v251
	v_and_b32_e32 v48, 1, v252
	v_lshl_or_b32 v251, v48, 6, v251
	v_add_u32_e32 v251, v251, v171
	s_waitcnt vmcnt(0)
	s_branch .LBB0_510
; __device__ __forceinline__ unsigned short f2bf(float x) { return (unsigned short)(cvtpk(x, x) & 0xffffu); }
; #define SBAR() __builtin_amdgcn_sched_barrier(0)
; __device__ __forceinline__ int crow(int r, int hi) { return (r & 3) + 8 * (r >> 2) + 4 * hi; }
; __device__ __forceinline__ void attn_phase(const bf16* __restrict__ qbase, const bf16* __restrict__ Kbase, const bf16* __restrict__ Vbase, bf16* __restrict__ mixbase) {
;     ...
;     finishSM(pA0, pA1, pa0, pa1, pa2, pa3); SBAR();
;     PVD(vb0);
;     float rli[16];
;     #pragma unroll
;     for (int r = 0; r < 16; ++r) rli[r] = __builtin_amdgcn_rcpf(__shfl(o2[r], hi * 32));
;     unsigned short* Ow = (unsigned short*)Ob + (long)(wid * 32) * 1024;
;     #pragma unroll
;     for (int r = 0; r < 16; ++r) { int orow = crow(r, hi);
;       #pragma unroll
;       for (int d0 = 0; d0 < 2; ++d0) Ow[(long)orow * 1024 + d0 * 32 + r32] = f2bf(o[d0][r] * rli[r]); }
.LBB0_509:
	v_exp_f32_e32 v56, v152
	v_exp_f32_e32 v57, v153
	v_exp_f32_e32 v58, v150
	v_exp_f32_e32 v59, v151
	v_exp_f32_e32 v60, v148
	v_exp_f32_e32 v61, v149
	v_exp_f32_e32 v62, v146
	v_exp_f32_e32 v63, v147
	v_exp_f32_e32 v64, v144
	v_exp_f32_e32 v65, v145
	v_exp_f32_e32 v66, v158
	v_exp_f32_e32 v67, v159
	v_exp_f32_e32 v68, v156
	v_exp_f32_e32 v69, v157
	v_exp_f32_e32 v70, v154
	v_exp_f32_e32 v71, v155
	v_cvt_pk_bf16_f32 v48, v226, v230
	v_cvt_pk_bf16_f32 v49, v227, v231
	v_cvt_pk_bf16_f32 v50, v228, v232
	v_cvt_pk_bf16_f32 v51, v225, v229
	v_cvt_pk_bf16_f32 v52, v206, v223
	v_cvt_pk_bf16_f32 v53, v207, v224
	v_cvt_pk_bf16_f32 v54, v205, v222
	v_cvt_pk_bf16_f32 v55, v204, v221
	v_cvt_pk_bf16_f32 v56, v56, v57
	v_cvt_pk_bf16_f32 v57, v58, v59
	v_cvt_pk_bf16_f32 v58, v60, v61
	v_cvt_pk_bf16_f32 v59, v62, v63
	v_cvt_pk_bf16_f32 v60, v64, v65
	v_cvt_pk_bf16_f32 v61, v66, v67
	v_cvt_pk_bf16_f32 v62, v68, v69
	v_cvt_pk_bf16_f32 v63, v70, v71
	s_nop 0
	v_permlane32_swap_b32_e32 v48, v50
	v_permlane32_swap_b32_e32 v49, v51
	v_permlane32_swap_b32_e32 v52, v54
	v_permlane32_swap_b32_e32 v53, v55
	v_permlane32_swap_b32_e32 v56, v58
	v_permlane32_swap_b32_e32 v57, v59
	v_permlane32_swap_b32_e32 v60, v62
	v_permlane32_swap_b32_e32 v61, v63
	ds_read_b64_tr_b16 v[64:65], v212 offset:0
	ds_read_b64_tr_b16 v[66:67], v212 offset:0x400
	ds_read_b64_tr_b16 v[68:69], v212 offset:0x800
	ds_read_b64_tr_b16 v[70:71], v212 offset:0xc00
	ds_read_b64_tr_b16 v[72:73], v212 offset:0x1000
	ds_read_b64_tr_b16 v[74:75], v212 offset:0x1400
	ds_read_b64_tr_b16 v[76:77], v212 offset:0x1800
	ds_read_b64_tr_b16 v[78:79], v212 offset:0x1c00
	s_waitcnt lgkmcnt(0)
	s_nop 0
	v_mfma_f32_32x32x16_bf16 v[0:15], v[48:51], v[64:67], v[0:15]
	ds_read_b64_tr_b16 v[64:65], v212 offset:0x200
	ds_read_b64_tr_b16 v[66:67], v212 offset:0x600
	v_mfma_f32_32x32x16_bf16 v[0:15], v[52:55], v[68:71], v[0:15]
	ds_read_b64_tr_b16 v[68:69], v212 offset:0xa00
	ds_read_b64_tr_b16 v[70:71], v212 offset:0xe00
	v_mfma_f32_32x32x16_bf16 v[0:15], v[56:59], v[72:75], v[0:15]
	ds_read_b64_tr_b16 v[72:73], v212 offset:0x1200
	ds_read_b64_tr_b16 v[74:75], v212 offset:0x1600
	ds_read_b64_tr_b16 v[132:133], v212 offset:0x1a00
	ds_read_b64_tr_b16 v[134:135], v212 offset:0x1e00
	s_waitcnt lgkmcnt(0)
	v_mfma_f32_32x32x16_bf16 v[0:15], v[60:63], v[76:79], v[0:15]
	v_mfma_f32_16x16x32_bf16 v[32:35], v[48:51], v[116:119], v[32:35]
	v_mov_b32_e32 v181, v165
	v_mov_b64_e32 v[142:143], v[126:127]
	v_mov_b64_e32 v[138:139], v[130:131]
	s_mov_b64 s[60:61], s[30:31]
	s_mov_b64 s[6:7], s[28:29]
	v_mov_b64_e32 v[140:141], v[124:125]
	v_mov_b64_e32 v[136:137], v[128:129]
	v_mfma_f32_16x16x32_bf16 v[32:35], v[52:55], v[116:119], v[32:35]
	v_mfma_f32_32x32x16_bf16 v[16:31], v[48:51], v[64:67], v[16:31]
	v_mfma_f32_16x16x32_bf16 v[32:35], v[56:59], v[116:119], v[32:35]
	v_mfma_f32_32x32x16_bf16 v[16:31], v[52:55], v[68:71], v[16:31]
	v_mfma_f32_16x16x32_bf16 v[32:35], v[60:63], v[116:119], v[32:35]
	v_mfma_f32_32x32x16_bf16 v[16:31], v[56:59], v[72:75], v[16:31]
	s_nop 10
	v_lshrrev_b32_e32 v48, 1, v215
	v_add_u32_e32 v49, 0x80, v48
	v_add_u32_e32 v50, 4, v48
	v_add_u32_e32 v51, 0x84, v48
	ds_bpermute_b32 v76, v48, v32
	ds_bpermute_b32 v77, v48, v33
	ds_bpermute_b32 v36, v49, v32
	ds_bpermute_b32 v37, v49, v33
	ds_bpermute_b32 v38, v49, v34
	ds_bpermute_b32 v39, v49, v35
	ds_bpermute_b32 v40, v50, v32
	ds_bpermute_b32 v41, v50, v33
	ds_bpermute_b32 v42, v50, v34
	ds_bpermute_b32 v46, v50, v35
	ds_bpermute_b32 v47, v51, v32
	ds_bpermute_b32 v43, v51, v33
	ds_bpermute_b32 v44, v51, v34
	ds_bpermute_b32 v45, v51, v35
	ds_bpermute_b32 v34, v48, v34
	ds_bpermute_b32 v35, v48, v35
	s_waitcnt lgkmcnt(0)
	v_rcp_f32_e32 v76, v76
	v_rcp_f32_e32 v77, v77
	v_rcp_f32_e32 v34, v34
	v_rcp_f32_e32 v35, v35
	v_rcp_f32_e32 v36, v36
	v_rcp_f32_e32 v37, v37
	v_rcp_f32_e32 v38, v38
	v_rcp_f32_e32 v39, v39
	v_rcp_f32_e32 v40, v40
	v_rcp_f32_e32 v41, v41
	v_rcp_f32_e32 v42, v42
	v_rcp_f32_e32 v46, v46
	v_rcp_f32_e32 v47, v47
	v_rcp_f32_e32 v43, v43
	v_rcp_f32_e32 v44, v44
	v_rcp_f32_e32 v45, v45
	s_waitcnt lgkmcnt(4)
	s_waitcnt lgkmcnt(3)
	v_mfma_f32_32x32x16_bf16 v[16:31], v[60:63], v[132:135], v[16:31]
	s_waitcnt lgkmcnt(4)
	s_waitcnt lgkmcnt(3)
; __device__ __forceinline__ unsigned short f2bf(float x) { return (unsigned short)(cvtpk(x, x) & 0xffffu); }
; __device__ __forceinline__ int crow(int r, int hi) { return (r & 3) + 8 * (r >> 2) + 4 * hi; }
; __device__ __forceinline__ void attn_phase(const bf16* __restrict__ qbase, const bf16* __restrict__ Kbase, const bf16* __restrict__ Vbase, bf16* __restrict__ mixbase) {
;     ...
;     for (int r = 0; r < 16; ++r) rli[r] = __builtin_amdgcn_rcpf(__shfl(o2[r], hi * 32));
;     unsigned short* Ow = (unsigned short*)Ob + (long)(wid * 32) * 1024;
;     #pragma unroll
;     for (int r = 0; r < 16; ++r) { int orow = crow(r, hi);
;       #pragma unroll
;       for (int d0 = 0; d0 < 2; ++d0) Ow[(long)orow * 1024 + d0 * 32 + r32] = f2bf(o[d0][r] * rli[r]); }
	v_lshl_add_u64 v[32:33], s[72:73], 0, v[172:173]
	v_lshl_add_u64 v[32:33], v[32:33], 0, v[180:181]
	v_mul_f32_e32 v0, v0, v76
	v_lshl_add_u64 v[32:33], v[32:33], 0, v[174:175]
	v_cvt_pk_bf16_f32 v0, v0, v0
	global_store_short v[32:33], v0, off
	v_mul_f32_e32 v0, v16, v76
	v_cvt_pk_bf16_f32 v0, v0, v0
	global_store_short v[32:33], v0, off offset:64
	v_mul_f32_e32 v0, v1, v77
	v_cvt_pk_bf16_f32 v0, v0, v0
	global_store_short v[32:33], v0, off offset:2048
	v_mul_f32_e32 v0, v17, v77
	v_cvt_pk_bf16_f32 v0, v0, v0
	global_store_short v[32:33], v0, off offset:2112
	v_mul_f32_e32 v0, v2, v34
	v_cvt_pk_bf16_f32 v2, v0, v0
	v_add_co_u32_e32 v0, vcc, s17, v32
	s_nop 0
	v_addc_co_u32_e32 v1, vcc, 0, v33, vcc
	global_store_short v[0:1], v2, off
	v_mul_f32_e32 v2, v18, v34
	v_cvt_pk_bf16_f32 v2, v2, v2
	global_store_short v[0:1], v2, off offset:64
	v_mul_f32_e32 v2, v3, v35
	v_cvt_pk_bf16_f32 v2, v2, v2
	global_store_short v[0:1], v2, off offset:2048
	v_mul_f32_e32 v2, v19, v35
	v_cvt_pk_bf16_f32 v2, v2, v2
	global_store_short v[0:1], v2, off offset:2112
	v_mul_f32_e32 v0, v4, v36
	v_cvt_pk_bf16_f32 v4, v0, v0
	v_add_co_u32_e32 v0, vcc, s12, v32
	s_waitcnt lgkmcnt(1)
	v_addc_co_u32_e32 v1, vcc, 0, v33, vcc
	v_add_co_u32_e32 v2, vcc, s33, v32
	s_nop 0
	v_addc_co_u32_e32 v3, vcc, 0, v33, vcc
	global_store_short v[2:3], v4, off offset:-4096
	v_mul_f32_e32 v4, v20, v36
	s_waitcnt lgkmcnt(1)
	v_cvt_pk_bf16_f32 v4, v4, v4
	global_store_short v[0:1], v4, off offset:64
	v_mul_f32_e32 v4, v5, v37
	v_cvt_pk_bf16_f32 v4, v4, v4
	global_store_short v[0:1], v4, off offset:2048
	v_mul_f32_e32 v4, v21, v37
	s_waitcnt lgkmcnt(1)
	v_cvt_pk_bf16_f32 v4, v4, v4
	global_store_short v[0:1], v4, off offset:2112
	v_mul_f32_e32 v0, v6, v38
	v_cvt_pk_bf16_f32 v0, v0, v0
	global_store_short v[2:3], v0, off
	v_mul_f32_e32 v0, v22, v38
	v_cvt_pk_bf16_f32 v0, v0, v0
	s_waitcnt lgkmcnt(0)
	global_store_short v[2:3], v0, off offset:64
	v_mul_f32_e32 v0, v7, v39
	v_cvt_pk_bf16_f32 v0, v0, v0
	global_store_short v[2:3], v0, off offset:2048
	v_mul_f32_e32 v0, v23, v39
	v_cvt_pk_bf16_f32 v0, v0, v0
	global_store_short v[2:3], v0, off offset:2112
	v_mul_f32_e32 v0, v8, v40
	v_cvt_pk_bf16_f32 v4, v0, v0
	v_add_co_u32_e32 v0, vcc, s3, v32
	s_waitcnt lgkmcnt(1)
	v_addc_co_u32_e32 v1, vcc, 0, v33, vcc
	v_add_co_u32_e32 v2, vcc, s13, v32
	s_waitcnt lgkmcnt(0)
	v_addc_co_u32_e32 v3, vcc, 0, v33, vcc
	global_store_short v[2:3], v4, off offset:-4096
	v_mul_f32_e32 v4, v24, v40
	v_cvt_pk_bf16_f32 v4, v4, v4
	global_store_short v[0:1], v4, off offset:64
	v_mul_f32_e32 v4, v9, v41
	v_cvt_pk_bf16_f32 v4, v4, v4
	global_store_short v[0:1], v4, off offset:2048
	v_mul_f32_e32 v4, v25, v41
	v_cvt_pk_bf16_f32 v4, v4, v4
	global_store_short v[0:1], v4, off offset:2112
	v_mul_f32_e32 v0, v10, v42
	v_cvt_pk_bf16_f32 v0, v0, v0
	global_store_short v[2:3], v0, off
	v_mul_f32_e32 v0, v26, v42
	v_cvt_pk_bf16_f32 v0, v0, v0
	global_store_short v[2:3], v0, off offset:64
	v_mul_f32_e32 v0, v11, v46
	v_cvt_pk_bf16_f32 v0, v0, v0
	global_store_short v[2:3], v0, off offset:2048
	v_mul_f32_e32 v0, v27, v46
	v_cvt_pk_bf16_f32 v0, v0, v0
	global_store_short v[2:3], v0, off offset:2112
	v_mul_f32_e32 v0, v12, v47
	v_cvt_pk_bf16_f32 v4, v0, v0
	v_add_co_u32_e32 v0, vcc, s16, v32
	s_nop 0
	v_addc_co_u32_e32 v1, vcc, 0, v33, vcc
	v_add_co_u32_e32 v2, vcc, s62, v32
	s_nop 0
	v_addc_co_u32_e32 v3, vcc, 0, v33, vcc
	global_store_short v[2:3], v4, off offset:-4096
	v_mul_f32_e32 v4, v28, v47
	v_cvt_pk_bf16_f32 v4, v4, v4
	global_store_short v[0:1], v4, off offset:64
	v_mul_f32_e32 v4, v13, v43
	v_cvt_pk_bf16_f32 v4, v4, v4
	global_store_short v[0:1], v4, off offset:2048
	v_mul_f32_e32 v4, v29, v43
	v_cvt_pk_bf16_f32 v4, v4, v4
	global_store_short v[0:1], v4, off offset:2112
	v_mul_f32_e32 v0, v14, v44
	v_cvt_pk_bf16_f32 v0, v0, v0
	global_store_short v[2:3], v0, off
	v_mul_f32_e32 v0, v30, v44
	v_cvt_pk_bf16_f32 v0, v0, v0
	global_store_short v[2:3], v0, off offset:64
	v_mul_f32_e32 v0, v15, v45
	v_cvt_pk_bf16_f32 v0, v0, v0
	v_mov_b64_e32 v[134:135], v[122:123]
	global_store_short v[2:3], v0, off offset:2048
	v_mul_f32_e32 v0, v31, v45
	s_and_b64 vcc, exec, s[70:71]
	s_mov_b64 s[72:73], s[68:69]
	v_mov_b64_e32 v[132:133], v[120:121]
	v_cvt_pk_bf16_f32 v0, v0, v0
	global_store_short v[2:3], v0, off offset:2112
	s_cbranch_vccnz .LBB0_541

; #define SWRITE(b, i) do { *(bf16x8*)(V_lds + (b) * SHM_VT + vst) = sr_[i].v0; \
;     *(bf16x8*)(K_lds + (b) * SHM_KT + kst0) = sr_[i].k0; *(bf16x8*)(K_lds + (b) * SHM_KT + kst1) = sr_[i].k1; } while (0)
; #define SWAIT() asm volatile("s_waitcnt vmcnt(3)" ::: "memory")
; #define RESC(a) do { if (__any((a) < 1.f)) { if (hi == 0) al_l[r32] = (a); asm volatile("s_waitcnt lgkmcnt(0)" ::: "memory"); \
;     _Pragma("unroll") for (int r = 0; r < 16; ++r) { const float a_ = al_l[crow(r, hi)]; o[0][r] *= a_; o[1][r] *= a_; o2[r] *= a_; } } } while (0)
; __device__ __forceinline__ void attn_phase(const bf16* __restrict__ qbase, const bf16* __restrict__ Kbase, const bf16* __restrict__ Vbase, bf16* __restrict__ mixbase) {
;     ...
;       PVD(vb0); partialSM(pB0, pB1, m_reg, mnB, alB);
;       __syncthreads(); SWAIT(); SWRITE(0, SE);
;       RESC(alB); __syncthreads();
.LBB0_519:
	ds_read_b64_tr_b16 v[132:133], v212 offset:0
	ds_read_b64_tr_b16 v[134:135], v212 offset:0x400
	ds_read_b64_tr_b16 v[136:137], v212 offset:0x800
	ds_read_b64_tr_b16 v[138:139], v212 offset:0xc00
	ds_read_b64_tr_b16 v[140:141], v212 offset:0x1000
	ds_read_b64_tr_b16 v[142:143], v212 offset:0x1400
	ds_read_b64_tr_b16 v[222:223], v212 offset:0x1800
	ds_read_b64_tr_b16 v[224:225], v212 offset:0x1c00
	s_waitcnt lgkmcnt(0)
	s_nop 0
	v_mfma_f32_32x32x16_bf16 v[0:15], v[148:151], v[132:135], v[0:15]
	ds_read_b64_tr_b16 v[132:133], v212 offset:0x200
	ds_read_b64_tr_b16 v[134:135], v212 offset:0x600
	v_mfma_f32_32x32x16_bf16 v[0:15], v[144:147], v[136:139], v[0:15]
	ds_read_b64_tr_b16 v[136:137], v212 offset:0xa00
	ds_read_b64_tr_b16 v[138:139], v212 offset:0xe00
	v_mfma_f32_32x32x16_bf16 v[0:15], v[152:155], v[140:143], v[0:15]
	ds_read_b64_tr_b16 v[140:141], v212 offset:0x1200
	ds_read_b64_tr_b16 v[142:143], v212 offset:0x1600
	ds_read_b64_tr_b16 v[226:227], v212 offset:0x1a00
	ds_read_b64_tr_b16 v[228:229], v212 offset:0x1e00
	s_waitcnt lgkmcnt(0)
	v_mfma_f32_32x32x16_bf16 v[0:15], v[156:159], v[222:225], v[0:15]
	v_mfma_f32_32x32x16_bf16 v[16:31], v[148:151], v[132:135], v[16:31]
	v_max_f32_e32 v132, v65, v65
	v_max_f32_e32 v133, v64, v64
	v_max_f32_e32 v132, v133, v132
	v_max3_f32 v132, v132, v66, v67
	v_max3_f32 v132, v132, v68, v69
	v_max3_f32 v132, v132, v70, v71
	v_max3_f32 v132, v132, v72, v73
	v_mfma_f32_16x16x32_bf16 v[32:35], v[148:151], v[116:119], v[32:35]
	v_max3_f32 v132, v132, v74, v75
	v_max3_f32 v132, v132, v76, v77
	v_max3_f32 v132, v132, v78, v79
	v_max3_f32 v132, v132, v48, v49
	v_max3_f32 v132, v132, v50, v51
	v_max3_f32 v132, v132, v52, v53
	v_max3_f32 v132, v132, v54, v55
	v_mfma_f32_32x32x16_bf16 v[16:31], v[144:147], v[136:139], v[16:31]
	v_max3_f32 v132, v132, v56, v57
	v_max3_f32 v132, v132, v58, v59
	v_max3_f32 v132, v132, v60, v61
	v_max3_f32 v132, v132, v62, v63
	v_mov_b32_e32 v133, v132
	s_nop 1
	v_permlane32_swap_b32_e32 v132, v133
	v_mfma_f32_16x16x32_bf16 v[32:35], v[144:147], v[116:119], v[32:35]
	v_max_f32_e32 v133, v133, v133
	v_max_f32_e32 v132, v132, v132
	v_max_f32_e32 v132, v132, v133
	v_max_f32_e32 v134, v181, v181
	v_sub_f32_e32 v133, v132, v181
	v_max_f32_e32 v132, v134, v132
	v_sub_f32_e32 v134, v181, v132
	v_mfma_f32_32x32x16_bf16 v[16:31], v[152:155], v[140:143], v[16:31]
	v_mul_f32_e32 v134, 0x3e16c740, v134
	v_exp_f32_e32 v134, v134
	v_cmp_ge_f32_e32 vcc, s9, v133
	s_cmp_eq_u64 vcc, exec
	s_cselect_b64 s[0:1], -1, 0
	s_barrier
	v_mfma_f32_16x16x32_bf16 v[32:35], v[152:155], v[116:119], v[32:35]
	s_waitcnt vmcnt(3)
	v_cndmask_b32_e64 v133, v134, 1.0, s[0:1]
	v_cmp_gt_f32_e32 vcc, 1.0, v133
	ds_write_b128 v216, v[112:115]
	ds_write_b128 v217, v[104:107] offset:16384
	ds_write_b128 v218, v[108:111] offset:16384
	v_mfma_f32_32x32x16_bf16 v[16:31], v[156:159], v[226:229], v[16:31]
	v_mfma_f32_16x16x32_bf16 v[32:35], v[156:159], v[116:119], v[32:35]
	s_cbranch_vccz .LBB0_523
	s_and_saveexec_b64 s[48:49], s[4:5]
	ds_write_b32 v213, v133 offset:43136
	s_or_b64 exec, exec, s[48:49]
	s_waitcnt lgkmcnt(0)
	v_add_u32_e32 v133, v171, v170
	ds_read_b128 v[36:39], v251 offset:43136
	ds_read_b128 v[134:137], v133 offset:43232
	ds_read_b128 v[138:141], v133 offset:43200
	ds_read_b128 v[142:145], v133 offset:43168
	ds_read_b128 v[146:149], v133 offset:43136
	s_waitcnt lgkmcnt(3)
	v_pk_mul_f32 v[12:13], v[12:13], v[134:135]
	s_waitcnt lgkmcnt(2)
	v_pk_mul_f32 v[8:9], v[8:9], v[138:139]
	s_waitcnt lgkmcnt(1)
	v_pk_mul_f32 v[4:5], v[4:5], v[142:143]
	v_pk_mul_f32 v[14:15], v[14:15], v[136:137]
	v_pk_mul_f32 v[10:11], v[10:11], v[140:141]
	v_pk_mul_f32 v[6:7], v[6:7], v[144:145]
	s_waitcnt lgkmcnt(0)
	v_pk_mul_f32 v[2:3], v[2:3], v[148:149]
	v_pk_mul_f32 v[0:1], v[0:1], v[146:147]
	v_pk_mul_f32 v[28:29], v[28:29], v[134:135]
	v_pk_mul_f32 v[24:25], v[24:25], v[138:139]
	v_pk_mul_f32 v[20:21], v[20:21], v[142:143]
	v_pk_mul_f32 v[30:31], v[30:31], v[136:137]
	v_pk_mul_f32 v[26:27], v[26:27], v[140:141]
	v_pk_mul_f32 v[22:23], v[22:23], v[144:145]
	v_pk_mul_f32 v[18:19], v[18:19], v[148:149]
	v_pk_mul_f32 v[16:17], v[16:17], v[146:147]
	v_pk_mul_f32 v[32:33], v[32:33], v[36:37]
	v_pk_mul_f32 v[34:35], v[34:35], v[38:39]

; #define SWRITE(b, i) do { *(bf16x8*)(V_lds + (b) * SHM_VT + vst) = sr_[i].v0; \
;     *(bf16x8*)(K_lds + (b) * SHM_KT + kst0) = sr_[i].k0; *(bf16x8*)(K_lds + (b) * SHM_KT + kst1) = sr_[i].k1; } while (0)
; #define SWAIT() asm volatile("s_waitcnt vmcnt(3)" ::: "memory")
; #define RESC(a) do { if (__any((a) < 1.f)) { if (hi == 0) al_l[r32] = (a); asm volatile("s_waitcnt lgkmcnt(0)" ::: "memory"); \
;     _Pragma("unroll") for (int r = 0; r < 16; ++r) { const float a_ = al_l[crow(r, hi)]; o[0][r] *= a_; o[1][r] *= a_; o2[r] *= a_; } } } while (0)
; __device__ __forceinline__ void attn_phase(const bf16* __restrict__ qbase, const bf16* __restrict__ Kbase, const bf16* __restrict__ Vbase, bf16* __restrict__ mixbase) {
;     ...
;       PVD(vb0 + SHM_VT); partialSM(pA0, pA1, m_reg, mnA, alA);
;       __syncthreads(); SWAIT(); if (j + 2 < NT) SWRITE(1, SO);
;       RESC(alA); __syncthreads();
.LBB0_533:
	ds_read_b64_tr_b16 v[150:151], v214 offset:0
	ds_read_b64_tr_b16 v[152:153], v214 offset:0x400
	ds_read_b64_tr_b16 v[154:155], v214 offset:0x800
	ds_read_b64_tr_b16 v[156:157], v214 offset:0xc00
	ds_read_b64_tr_b16 v[204:205], v214 offset:0x1000
	ds_read_b64_tr_b16 v[206:207], v214 offset:0x1400
	ds_read_b64_tr_b16 v[222:223], v214 offset:0x1800
	ds_read_b64_tr_b16 v[224:225], v214 offset:0x1c00
	s_waitcnt lgkmcnt(0)
	s_nop 0
	v_mfma_f32_32x32x16_bf16 v[0:15], v[132:135], v[150:153], v[0:15]
	ds_read_b64_tr_b16 v[150:151], v214 offset:0x200
	ds_read_b64_tr_b16 v[152:153], v214 offset:0x600
	v_mfma_f32_32x32x16_bf16 v[0:15], v[136:139], v[154:157], v[0:15]
	ds_read_b64_tr_b16 v[154:155], v214 offset:0xa00
	ds_read_b64_tr_b16 v[156:157], v214 offset:0xe00
	v_mfma_f32_32x32x16_bf16 v[0:15], v[140:143], v[204:207], v[0:15]
	ds_read_b64_tr_b16 v[204:205], v214 offset:0x1200
	ds_read_b64_tr_b16 v[206:207], v214 offset:0x1600
	ds_read_b64_tr_b16 v[226:227], v214 offset:0x1a00
	ds_read_b64_tr_b16 v[228:229], v214 offset:0x1e00
	s_waitcnt lgkmcnt(0)
	v_mfma_f32_32x32x16_bf16 v[0:15], v[144:147], v[222:225], v[0:15]
	v_mfma_f32_32x32x16_bf16 v[16:31], v[132:135], v[150:153], v[16:31]
	v_max_f32_e32 v149, v49, v49
	v_max_f32_e32 v150, v48, v48
	v_max_f32_e32 v149, v150, v149
	v_max3_f32 v149, v149, v50, v51
	v_max3_f32 v149, v149, v52, v53
	v_max3_f32 v149, v149, v54, v55
	v_max3_f32 v149, v149, v56, v57
	v_mfma_f32_16x16x32_bf16 v[32:35], v[132:135], v[116:119], v[32:35]
	v_max3_f32 v149, v149, v58, v59
	v_max3_f32 v149, v149, v60, v61
	v_max3_f32 v149, v149, v62, v63
	v_max3_f32 v149, v149, v64, v65
	v_max3_f32 v149, v149, v66, v67
	v_max3_f32 v132, v149, v68, v69
	v_max3_f32 v132, v132, v70, v71
	v_mfma_f32_32x32x16_bf16 v[16:31], v[136:139], v[154:157], v[16:31]
	v_max3_f32 v132, v132, v72, v73
	v_max3_f32 v132, v132, v74, v75
	v_max3_f32 v132, v132, v76, v77
	v_max3_f32 v132, v132, v78, v79
	v_mov_b32_e32 v133, v132
	s_nop 1
	v_permlane32_swap_b32_e32 v132, v133
	v_mfma_f32_16x16x32_bf16 v[32:35], v[136:139], v[116:119], v[32:35]
	v_max_f32_e32 v133, v133, v133
	v_max_f32_e32 v132, v132, v132
	v_max_f32_e32 v132, v132, v133
	v_sub_f32_e32 v133, v132, v148
	v_cmp_ge_f32_e32 vcc, s9, v133
	s_barrier
	v_mfma_f32_32x32x16_bf16 v[16:31], v[140:143], v[204:207], v[16:31]
	s_waitcnt vmcnt(3)
	s_cmp_eq_u64 vcc, exec
	s_cselect_b64 s[0:1], -1, 0
	s_andn2_b64 vcc, exec, s[44:45]
	v_mfma_f32_16x16x32_bf16 v[32:35], v[140:143], v[116:119], v[32:35]
	v_mfma_f32_32x32x16_bf16 v[16:31], v[144:147], v[226:229], v[16:31]
	v_mfma_f32_16x16x32_bf16 v[32:35], v[144:147], v[116:119], v[32:35]
	s_cbranch_vccnz .LBB0_535
	ds_write_b128 v216, v[128:131] offset:8192
	ds_write_b128 v217, v[120:123] offset:29696
	ds_write_b128 v218, v[124:127] offset:29696
.LBB0_535:
	v_max_f32_e32 v133, v148, v148
	v_max_f32_e32 v132, v133, v132
	v_sub_f32_e32 v133, v148, v132
	v_mul_f32_e32 v133, 0x3e16c740, v133
	v_exp_f32_e32 v133, v133
	s_nop 0
	v_cndmask_b32_e64 v133, v133, 1.0, s[0:1]
	v_cmp_gt_f32_e32 vcc, 1.0, v133
	s_cbranch_vccz .LBB0_539
	s_and_saveexec_b64 s[6:7], s[4:5]
	ds_write_b32 v213, v133 offset:43136
	s_or_b64 exec, exec, s[6:7]
	s_waitcnt lgkmcnt(0)
	v_add_u32_e32 v133, v171, v170
	ds_read_b128 v[36:39], v251 offset:43136
	ds_read_b128 v[134:137], v133 offset:43232
	ds_read_b128 v[138:141], v133 offset:43200
	ds_read_b128 v[142:145], v133 offset:43168
	ds_read_b128 v[150:153], v133 offset:43136
	s_waitcnt lgkmcnt(3)
	v_pk_mul_f32 v[12:13], v[12:13], v[134:135]
	s_waitcnt lgkmcnt(2)
	v_pk_mul_f32 v[8:9], v[8:9], v[138:139]
	s_waitcnt lgkmcnt(1)
	v_pk_mul_f32 v[4:5], v[4:5], v[142:143]
	v_pk_mul_f32 v[14:15], v[14:15], v[136:137]
	v_pk_mul_f32 v[10:11], v[10:11], v[140:141]
	v_pk_mul_f32 v[6:7], v[6:7], v[144:145]
	s_waitcnt lgkmcnt(0)
	v_pk_mul_f32 v[2:3], v[2:3], v[152:153]
	v_pk_mul_f32 v[0:1], v[0:1], v[150:151]
	v_pk_mul_f32 v[28:29], v[28:29], v[134:135]
	v_pk_mul_f32 v[24:25], v[24:25], v[138:139]
	v_pk_mul_f32 v[20:21], v[20:21], v[142:143]
	v_pk_mul_f32 v[30:31], v[30:31], v[136:137]
	v_pk_mul_f32 v[26:27], v[26:27], v[140:141]
	v_pk_mul_f32 v[22:23], v[22:23], v[144:145]
	v_pk_mul_f32 v[18:19], v[18:19], v[152:153]
	v_pk_mul_f32 v[16:17], v[16:17], v[150:151]
	v_pk_mul_f32 v[32:33], v[32:33], v[36:37]
	v_pk_mul_f32 v[34:35], v[34:35], v[38:39]
